# norm phases v3: batch-major grid-stride quads (a wave stays in one batch, parameters loaded once), row loads double-buffered across quads
# speedup vs baseline: 1.0056x; 1.0056x over previous
; DI int get_tid() { int t = threadIdx.x; asm volatile("" : "+v"(t)); return t; }
; DI void phase_norm(const Params& p, int layer, int which  , int nrows) {
;   const int lane = get_tid() & 63, gw = blockIdx.x * 4 + (get_tid() >> 6), nw = gridDim.x * 4;
;   const float* g = (which == 0 ? p.norm1_g : p.norm2_g) + layer * D;
;   const float* mod = (const float*)(p.ws + OFF_MOD) + (size_t)layer * 9 * 6144;
;   bf16_t* H = (bf16_t*)(p.ws + OFF_H);
;   const bool first = (which == 0) && layer == 0;
;   for (int pr = gw; pr < (nrows >> 1); pr += nw) {
.Lnm_entry:
	v_writelane_b32 v254, s52, 0
	v_writelane_b32 v254, s53, 1
	v_writelane_b32 v254, s54, 2
	v_writelane_b32 v254, s55, 3
	v_writelane_b32 v254, s56, 4
	v_writelane_b32 v254, s57, 5
	v_writelane_b32 v254, s58, 6
	v_writelane_b32 v254, s59, 7
	v_writelane_b32 v254, s60, 8
	v_writelane_b32 v254, s61, 9
	v_writelane_b32 v254, s62, 10
	v_writelane_b32 v254, s63, 11
	v_writelane_b32 v254, s64, 12
	v_writelane_b32 v254, s65, 13
	v_writelane_b32 v254, s66, 14
	v_writelane_b32 v254, s67, 15
	v_writelane_b32 v254, s68, 16
	v_writelane_b32 v254, s69, 17
	v_writelane_b32 v254, s70, 18
	v_writelane_b32 v254, s71, 19
	v_writelane_b32 v254, s72, 20
	v_writelane_b32 v254, s73, 21
	v_writelane_b32 v254, s74, 22
	v_writelane_b32 v254, s75, 23
	v_writelane_b32 v254, s76, 24
	v_writelane_b32 v254, s77, 25
	v_writelane_b32 v254, s78, 26
	v_writelane_b32 v254, s79, 27
	v_writelane_b32 v254, s80, 28
	v_writelane_b32 v254, s81, 29
	v_writelane_b32 v254, s82, 30
	v_writelane_b32 v254, s83, 31
	v_writelane_b32 v254, s84, 32
	v_writelane_b32 v254, s85, 33
	v_writelane_b32 v254, s86, 34
	v_writelane_b32 v254, s87, 35
	v_writelane_b32 v254, s88, 36
	v_writelane_b32 v254, s89, 37
	v_writelane_b32 v254, s90, 38
	v_writelane_b32 v254, s91, 39
	s_mov_b32 s52, s100
	s_mov_b32 s53, s101
	v_lshrrev_b32_e32 v132, 6, v143
	v_readlane_b32 s0, v255, 0
	s_nop 0
	v_readfirstlane_b32 s1, v132
	s_nop 3
	s_lshl_b32 s0, s0, 2
	s_add_u32 s0, s0, s1
	s_lshr_b32 s1, s0, 8
	s_lshl_b32 s1, s1, 10
	s_and_b32 s12, s0, 255
	s_add_u32 s54, s1, s12
	s_mov_b32 s78, 4
	s_mov_b32 s81, 0
	s_add_u32 s86, s0, 8192
	s_cmp_eq_u32 s52, 1
	s_cbranch_scc0 .Lnm_nq_1a
	s_cmp_eq_u32 s53, 0
	s_cbranch_scc0 .Lnm_nq_1
.Lnm_nq_1a:
	s_cmp_lt_u32 s0, 512
	s_cbranch_scc0 .Lnm_nq_1
	s_mov_b32 s78, 5

; DI void phase_norm(const Params& p, int layer, int which  , int nrows) {
;     ...
;   for (int pr = gw; pr < (nrows >> 1); pr += nw) {
;     const int row = pr * 2;
;     const float* xr0 = xold_ptr(p, layer, first, row);
;     const float* xr1 = xold_ptr(p, layer, first, row + 1);
.Lnm_same_9:
	s_add_u32 s81, s81, 1
	s_cmp_lt_u32 s81, s78
	s_cbranch_scc0 .Lnm_nonext_12
	s_add_u32 s80, s54, 256
	s_cmp_eq_u32 s81, 4
	s_cselect_b32 s80, s86, s80
	s_lshl_b32 s0, s80, 2
	s_cmp_lt_u32 s0, 0x8000
	s_cbranch_scc0 .Lnm_ctx_14
	s_lshl_b32 s0, s0, 12
	s_add_u32 s64, s60, s0
	s_addc_u32 s65, s61, 0
	s_branch .Lnm_j_15

; DI unsigned pack2(float lo, float hi) { f32x2_t v = {lo, hi}; bf16x2_t r = __builtin_convertvector(v, bf16x2_t); return __builtin_bit_cast(unsigned, r); }
; DI void phase_norm(const Params& p, int layer, int which  , int nrows) {
;     ...
; #pragma unroll
;     for (int i = 0; i < 4; ++i) {
;       ss0 += v[0][i].x * v[0][i].x + v[0][i].y * v[0][i].y + v[0][i].z * v[0][i].z + v[0][i].w * v[0][i].w;
;       ss1 += v[1][i].x * v[1][i].x + v[1][i].y * v[1][i].y + v[1][i].z * v[1][i].z + v[1][i].w * v[1][i].w;
;     }
;     ss0 = wave_sum(ss0); ss1 = wave_sum(ss1);
;     const float rstd0 = rsqrtf(ss0 * (1.0f / D) + 1e-6f), rstd1 = rsqrtf(ss1 * (1.0f / D) + 1e-6f);
; #pragma unroll
;     for (int k = 0; k < 2; ++k) {
;       const float rstd = k == 0 ? rstd0 : rstd1;
; #pragma unroll
;       for (int i = 0; i < 4; ++i) {
;         const int col = 4 * (lane + 64 * i);
;         float y0 = v[k][i].x * rstd * gg[i].x * (1.f + s4[i].x) + h4[i].x;
;         float y1 = v[k][i].y * rstd * gg[i].y * (1.f + s4[i].y) + h4[i].y;
;         float y2 = v[k][i].z * rstd * gg[i].z * (1.f + s4[i].z) + h4[i].z;
;         float y3 = v[k][i].w * rstd * gg[i].w * (1.f + s4[i].w) + h4[i].w;
;         uint2 w; w.x = pack2(y0, y1); w.y = pack2(y2, y3);
;         *(uint2*)(H + (size_t)(row + k) * D + col) = w;
.Lnm_nj_13:
	s_lshl_b32 s0, s57, 6
	s_add_u32 s0, s0, 0x15980000
	s_add_u32 s66, s24, s0
	s_addc_u32 s67, s25, 0
	v_mul_f32_e32 v128, v0, v0
	v_fmac_f32_e32 v128, v1, v1
	v_fmac_f32_e32 v128, v2, v2
	v_fmac_f32_e32 v128, v3, v3
	v_fmac_f32_e32 v128, v4, v4
	v_fmac_f32_e32 v128, v5, v5
	v_fmac_f32_e32 v128, v6, v6
	v_fmac_f32_e32 v128, v7, v7
	v_fmac_f32_e32 v128, v8, v8
	v_fmac_f32_e32 v128, v9, v9
	v_fmac_f32_e32 v128, v10, v10
	v_fmac_f32_e32 v128, v11, v11
	v_fmac_f32_e32 v128, v12, v12
	v_fmac_f32_e32 v128, v13, v13
	v_fmac_f32_e32 v128, v14, v14
	v_fmac_f32_e32 v128, v15, v15
	v_mul_f32_e32 v129, v16, v16
	v_fmac_f32_e32 v129, v17, v17
	v_fmac_f32_e32 v129, v18, v18
	v_fmac_f32_e32 v129, v19, v19
	v_fmac_f32_e32 v129, v20, v20
	v_fmac_f32_e32 v129, v21, v21
	v_fmac_f32_e32 v129, v22, v22
	v_fmac_f32_e32 v129, v23, v23
	v_fmac_f32_e32 v129, v24, v24
	v_fmac_f32_e32 v129, v25, v25
	v_fmac_f32_e32 v129, v26, v26
	v_fmac_f32_e32 v129, v27, v27
	v_fmac_f32_e32 v129, v28, v28
	v_fmac_f32_e32 v129, v29, v29
	v_fmac_f32_e32 v129, v30, v30
	v_fmac_f32_e32 v129, v31, v31
	v_mul_f32_e32 v130, v32, v32
	v_fmac_f32_e32 v130, v33, v33
	v_fmac_f32_e32 v130, v34, v34
	v_fmac_f32_e32 v130, v35, v35
	v_fmac_f32_e32 v130, v36, v36
	v_fmac_f32_e32 v130, v37, v37
	v_fmac_f32_e32 v130, v38, v38
	v_fmac_f32_e32 v130, v39, v39
	v_fmac_f32_e32 v130, v40, v40
	v_fmac_f32_e32 v130, v41, v41
	v_fmac_f32_e32 v130, v42, v42
	v_fmac_f32_e32 v130, v43, v43
	v_fmac_f32_e32 v130, v44, v44
	v_fmac_f32_e32 v130, v45, v45
	v_fmac_f32_e32 v130, v46, v46
	v_fmac_f32_e32 v130, v47, v47
	v_mul_f32_e32 v131, v48, v48
	v_fmac_f32_e32 v131, v49, v49
	v_fmac_f32_e32 v131, v50, v50
	v_fmac_f32_e32 v131, v51, v51
	v_fmac_f32_e32 v131, v52, v52
	v_fmac_f32_e32 v131, v53, v53
	v_fmac_f32_e32 v131, v54, v54
	v_fmac_f32_e32 v131, v55, v55
	v_fmac_f32_e32 v131, v56, v56
	v_fmac_f32_e32 v131, v57, v57
	v_fmac_f32_e32 v131, v58, v58
	v_fmac_f32_e32 v131, v59, v59
	v_fmac_f32_e32 v131, v60, v60
	v_fmac_f32_e32 v131, v61, v61
	v_fmac_f32_e32 v131, v62, v62
	v_fmac_f32_e32 v131, v63, v63
	v_add_f32_dpp v128, v128, v128 quad_perm:[1,0,3,2] row_mask:0xf bank_mask:0xf
	v_add_f32_dpp v129, v129, v129 quad_perm:[1,0,3,2] row_mask:0xf bank_mask:0xf
	v_add_f32_dpp v130, v130, v130 quad_perm:[1,0,3,2] row_mask:0xf bank_mask:0xf
	v_add_f32_dpp v131, v131, v131 quad_perm:[1,0,3,2] row_mask:0xf bank_mask:0xf
	v_add_f32_dpp v128, v128, v128 quad_perm:[2,3,0,1] row_mask:0xf bank_mask:0xf
	v_add_f32_dpp v129, v129, v129 quad_perm:[2,3,0,1] row_mask:0xf bank_mask:0xf
	v_add_f32_dpp v130, v130, v130 quad_perm:[2,3,0,1] row_mask:0xf bank_mask:0xf
	v_add_f32_dpp v131, v131, v131 quad_perm:[2,3,0,1] row_mask:0xf bank_mask:0xf
	v_add_f32_dpp v128, v128, v128 row_half_mirror row_mask:0xf bank_mask:0xf
	v_add_f32_dpp v129, v129, v129 row_half_mirror row_mask:0xf bank_mask:0xf
	v_add_f32_dpp v130, v130, v130 row_half_mirror row_mask:0xf bank_mask:0xf
	v_add_f32_dpp v131, v131, v131 row_half_mirror row_mask:0xf bank_mask:0xf
	v_add_f32_dpp v128, v128, v128 row_mirror row_mask:0xf bank_mask:0xf
	v_add_f32_dpp v129, v129, v129 row_mirror row_mask:0xf bank_mask:0xf
	v_add_f32_dpp v130, v130, v130 row_mirror row_mask:0xf bank_mask:0xf
	v_add_f32_dpp v131, v131, v131 row_mirror row_mask:0xf bank_mask:0xf
	s_nop 1
	v_readlane_b32 s82, v128, 0
	v_readlane_b32 s83, v128, 16
	v_readlane_b32 s84, v128, 32
	v_readlane_b32 s85, v128, 48
	s_nop 1
	v_mov_b32_e32 v132, s82
	v_add_f32_e32 v132, s83, v132
	v_add_f32_e32 v132, s84, v132
	v_add_f32_e32 v132, s85, v132
	v_readlane_b32 s82, v129, 0
	v_readlane_b32 s83, v129, 16
	v_readlane_b32 s84, v129, 32
	v_readlane_b32 s85, v129, 48
	s_nop 1
	v_mov_b32_e32 v133, s82
	v_add_f32_e32 v133, s83, v133
	v_add_f32_e32 v133, s84, v133
	v_add_f32_e32 v133, s85, v133
	v_readlane_b32 s82, v130, 0
	v_readlane_b32 s83, v130, 16
	v_readlane_b32 s84, v130, 32
	v_readlane_b32 s85, v130, 48
	s_nop 1
	v_mov_b32_e32 v134, s82
	v_add_f32_e32 v134, s83, v134
	v_add_f32_e32 v134, s84, v134
	v_add_f32_e32 v134, s85, v134
	v_readlane_b32 s82, v131, 0
	v_readlane_b32 s83, v131, 16
	v_readlane_b32 s84, v131, 32
	v_readlane_b32 s85, v131, 48
	s_nop 1
	v_mov_b32_e32 v135, s82
	v_add_f32_e32 v135, s83, v135
	v_add_f32_e32 v135, s84, v135
	v_add_f32_e32 v135, s85, v135
	s_mov_b32 s0, 0x3a800000
	v_fma_f32 v132, v132, s0, v153
	v_fma_f32 v133, v133, s0, v153
	v_fma_f32 v134, v134, s0, v153
	v_fma_f32 v135, v135, s0, v153
	v_rsq_f32_e32 v128, v132
	v_rsq_f32_e32 v129, v133
	v_rsq_f32_e32 v130, v134
	v_rsq_f32_e32 v131, v135
	v_mul_f32_e32 v0, v0, v128
	v_mul_f32_e32 v1, v1, v128
	v_mul_f32_e32 v2, v2, v128
	v_mul_f32_e32 v3, v3, v128
	v_fma_f32 v0, v0, v154, v170
	v_fma_f32 v1, v1, v155, v171
	v_fma_f32 v2, v2, v156, v172
	v_fma_f32 v3, v3, v157, v173
	v_cvt_pk_bf16_f32 v238, v0, v1
	v_cvt_pk_bf16_f32 v239, v2, v3
	global_store_dwordx2 v148, v[238:239], s[66:67]
	v_mul_f32_e32 v4, v4, v128
	v_mul_f32_e32 v5, v5, v128
	v_mul_f32_e32 v6, v6, v128
	v_mul_f32_e32 v7, v7, v128
	v_fma_f32 v4, v4, v158, v174
	v_fma_f32 v5, v5, v159, v175
	v_fma_f32 v6, v6, v160, v176
	v_fma_f32 v7, v7, v161, v177
	v_cvt_pk_bf16_f32 v240, v4, v5
	v_cvt_pk_bf16_f32 v241, v6, v7
	global_store_dwordx2 v149, v[240:241], s[66:67]
	v_mul_f32_e32 v8, v8, v128
	v_mul_f32_e32 v9, v9, v128
	v_mul_f32_e32 v10, v10, v128
	v_mul_f32_e32 v11, v11, v128
	v_fma_f32 v8, v8, v162, v178
	v_fma_f32 v9, v9, v163, v179
	v_fma_f32 v10, v10, v164, v180
	v_fma_f32 v11, v11, v165, v181
	v_cvt_pk_bf16_f32 v242, v8, v9
	v_cvt_pk_bf16_f32 v243, v10, v11
	global_store_dwordx2 v150, v[242:243], s[66:67]
	v_mul_f32_e32 v12, v12, v128
	v_mul_f32_e32 v13, v13, v128
; DI unsigned pack2(float lo, float hi) { f32x2_t v = {lo, hi}; bf16x2_t r = __builtin_convertvector(v, bf16x2_t); return __builtin_bit_cast(unsigned, r); }
; DI void phase_norm(const Params& p, int layer, int which  , int nrows) {
;     ...
;     const float* sh = mod + b9 * 6144 + (which == 0 ? 0 : 3) * 1024;
;     const float* sc = sh + 1024;
;     float4 gg[4], s4[4], h4[4];
; #pragma unroll
;     for (int i = 0; i < 4; ++i) {
;       const int col = 4 * (lane + 64 * i);
;       gg[i] = *(const float4*)(g + col); s4[i] = *(const float4*)(sc + col); h4[i] = *(const float4*)(sh + col);
;     ...
; #pragma unroll
;     for (int k = 0; k < 2; ++k) {
;       const float rstd = k == 0 ? rstd0 : rstd1;
; #pragma unroll
;       for (int i = 0; i < 4; ++i) {
;         const int col = 4 * (lane + 64 * i);
;         float y0 = v[k][i].x * rstd * gg[i].x * (1.f + s4[i].x) + h4[i].x;
;         float y1 = v[k][i].y * rstd * gg[i].y * (1.f + s4[i].y) + h4[i].y;
;         float y2 = v[k][i].z * rstd * gg[i].z * (1.f + s4[i].z) + h4[i].z;
;         float y3 = v[k][i].w * rstd * gg[i].w * (1.f + s4[i].w) + h4[i].w;
;         uint2 w; w.x = pack2(y0, y1); w.y = pack2(y2, y3);
;         *(uint2*)(H + (size_t)(row + k) * D + col) = w;
;       }
;     }
	v_mul_f32_e32 v14, v14, v128
	v_mul_f32_e32 v15, v15, v128
	v_fma_f32 v12, v12, v166, v182
	v_fma_f32 v13, v13, v167, v183
	v_fma_f32 v14, v14, v168, v184
	v_fma_f32 v15, v15, v169, v185
	v_cvt_pk_bf16_f32 v244, v12, v13
	v_cvt_pk_bf16_f32 v245, v14, v15
	global_store_dwordx2 v151, v[244:245], s[66:67]
	v_mul_f32_e32 v16, v16, v129
	v_mul_f32_e32 v17, v17, v129
	v_mul_f32_e32 v18, v18, v129
	v_mul_f32_e32 v19, v19, v129
	v_fma_f32 v16, v16, v154, v170
	v_fma_f32 v17, v17, v155, v171
	v_fma_f32 v18, v18, v156, v172
	v_fma_f32 v19, v19, v157, v173
	v_cvt_pk_bf16_f32 v246, v16, v17
	v_cvt_pk_bf16_f32 v247, v18, v19
	global_store_dwordx2 v148, v[246:247], s[66:67] offset:64
	v_mul_f32_e32 v20, v20, v129
	v_mul_f32_e32 v21, v21, v129
	v_mul_f32_e32 v22, v22, v129
	v_mul_f32_e32 v23, v23, v129
	v_fma_f32 v20, v20, v158, v174
	v_fma_f32 v21, v21, v159, v175
	v_fma_f32 v22, v22, v160, v176
	v_fma_f32 v23, v23, v161, v177
	v_cvt_pk_bf16_f32 v248, v20, v21
	v_cvt_pk_bf16_f32 v249, v22, v23
	global_store_dwordx2 v149, v[248:249], s[66:67] offset:64
	v_mul_f32_e32 v24, v24, v129
	v_mul_f32_e32 v25, v25, v129
	v_mul_f32_e32 v26, v26, v129
	v_mul_f32_e32 v27, v27, v129
	v_fma_f32 v24, v24, v162, v178
	v_fma_f32 v25, v25, v163, v179
	v_fma_f32 v26, v26, v164, v180
	v_fma_f32 v27, v27, v165, v181
	v_cvt_pk_bf16_f32 v238, v24, v25
	v_cvt_pk_bf16_f32 v239, v26, v27
	global_store_dwordx2 v150, v[238:239], s[66:67] offset:64
	v_mul_f32_e32 v28, v28, v129
	v_mul_f32_e32 v29, v29, v129
	v_mul_f32_e32 v30, v30, v129
	v_mul_f32_e32 v31, v31, v129
	v_fma_f32 v28, v28, v166, v182
	v_fma_f32 v29, v29, v167, v183
	v_fma_f32 v30, v30, v168, v184
	v_fma_f32 v31, v31, v169, v185
	v_cvt_pk_bf16_f32 v240, v28, v29
	v_cvt_pk_bf16_f32 v241, v30, v31
	global_store_dwordx2 v151, v[240:241], s[66:67] offset:64
	v_mul_f32_e32 v32, v32, v130
	v_mul_f32_e32 v33, v33, v130
	v_mul_f32_e32 v34, v34, v130
	v_mul_f32_e32 v35, v35, v130
	v_fma_f32 v32, v32, v154, v170
	v_fma_f32 v33, v33, v155, v171
	v_fma_f32 v34, v34, v156, v172
	v_fma_f32 v35, v35, v157, v173
	v_cvt_pk_bf16_f32 v242, v32, v33
	v_cvt_pk_bf16_f32 v243, v34, v35
	global_store_dwordx2 v148, v[242:243], s[66:67] offset:128
	v_mul_f32_e32 v36, v36, v130
	v_mul_f32_e32 v37, v37, v130
	v_mul_f32_e32 v38, v38, v130
	v_mul_f32_e32 v39, v39, v130
	v_fma_f32 v36, v36, v158, v174
	v_fma_f32 v37, v37, v159, v175
	v_fma_f32 v38, v38, v160, v176
	v_fma_f32 v39, v39, v161, v177
	v_cvt_pk_bf16_f32 v244, v36, v37
	v_cvt_pk_bf16_f32 v245, v38, v39
	global_store_dwordx2 v149, v[244:245], s[66:67] offset:128
	v_mul_f32_e32 v40, v40, v130
	v_mul_f32_e32 v41, v41, v130
	v_mul_f32_e32 v42, v42, v130
	v_mul_f32_e32 v43, v43, v130
	v_fma_f32 v40, v40, v162, v178
	v_fma_f32 v41, v41, v163, v179
	v_fma_f32 v42, v42, v164, v180
	v_fma_f32 v43, v43, v165, v181
	v_cvt_pk_bf16_f32 v246, v40, v41
	v_cvt_pk_bf16_f32 v247, v42, v43
	global_store_dwordx2 v150, v[246:247], s[66:67] offset:128
	v_mul_f32_e32 v44, v44, v130
	v_mul_f32_e32 v45, v45, v130
	v_mul_f32_e32 v46, v46, v130
	v_mul_f32_e32 v47, v47, v130
	v_fma_f32 v44, v44, v166, v182
	v_fma_f32 v45, v45, v167, v183
	v_fma_f32 v46, v46, v168, v184
	v_fma_f32 v47, v47, v169, v185
	v_cvt_pk_bf16_f32 v248, v44, v45
	v_cvt_pk_bf16_f32 v249, v46, v47
	global_store_dwordx2 v151, v[248:249], s[66:67] offset:128
	v_mul_f32_e32 v48, v48, v131
	v_mul_f32_e32 v49, v49, v131
	v_mul_f32_e32 v50, v50, v131
	v_mul_f32_e32 v51, v51, v131
	v_fma_f32 v48, v48, v154, v170
	v_fma_f32 v49, v49, v155, v171
	v_fma_f32 v50, v50, v156, v172
	v_fma_f32 v51, v51, v157, v173
	v_cvt_pk_bf16_f32 v238, v48, v49
	v_cvt_pk_bf16_f32 v239, v50, v51
	global_store_dwordx2 v148, v[238:239], s[66:67] offset:192
	v_mul_f32_e32 v52, v52, v131
	v_mul_f32_e32 v53, v53, v131
	v_mul_f32_e32 v54, v54, v131
	v_mul_f32_e32 v55, v55, v131
	v_fma_f32 v52, v52, v158, v174
	v_fma_f32 v53, v53, v159, v175
	v_fma_f32 v54, v54, v160, v176
	v_fma_f32 v55, v55, v161, v177
	v_cvt_pk_bf16_f32 v240, v52, v53
	v_cvt_pk_bf16_f32 v241, v54, v55
	global_store_dwordx2 v149, v[240:241], s[66:67] offset:192
	v_mul_f32_e32 v56, v56, v131
	v_mul_f32_e32 v57, v57, v131
	v_mul_f32_e32 v58, v58, v131
	v_mul_f32_e32 v59, v59, v131
	v_fma_f32 v56, v56, v162, v178
	v_fma_f32 v57, v57, v163, v179
	v_fma_f32 v58, v58, v164, v180
	v_fma_f32 v59, v59, v165, v181
	v_cvt_pk_bf16_f32 v242, v56, v57
	v_cvt_pk_bf16_f32 v243, v58, v59
	global_store_dwordx2 v150, v[242:243], s[66:67] offset:192
	v_mul_f32_e32 v60, v60, v131
	v_mul_f32_e32 v61, v61, v131
	v_mul_f32_e32 v62, v62, v131
	v_mul_f32_e32 v63, v63, v131
	v_fma_f32 v60, v60, v166, v182
	v_fma_f32 v61, v61, v167, v183
	v_fma_f32 v62, v62, v168, v184
	v_fma_f32 v63, v63, v169, v185
	v_cvt_pk_bf16_f32 v244, v60, v61
	v_cvt_pk_bf16_f32 v245, v62, v63
	global_store_dwordx2 v151, v[244:245], s[66:67] offset:192
	s_mov_b32 s54, s80
	s_cmp_lt_u32 s81, s78
	s_cbranch_scc0 .Lnm_done_5
	s_lshl_b32 s57, s54, 2
	s_lshr_b32 s1, s57, 12
	s_min_u32 s1, s1, 8
	s_cmp_eq_u32 s1, s79
	s_cbranch_scc1 .Lnm_same_16
	s_mov_b32 s79, s1
	s_mul_i32 s1, s1, 24576
	s_add_u32 s72, s70, s1
	s_addc_u32 s73, s71, 0
	s_add_u32 s74, s72, 0x1000
	s_addc_u32 s75, s73, 0
	global_load_dwordx4 v[154:157], v152, s[68:69] offset:0
	global_load_dwordx4 v[158:161], v152, s[68:69] offset:1024
	global_load_dwordx4 v[162:165], v152, s[68:69] offset:2048
	global_load_dwordx4 v[166:169], v152, s[68:69] offset:3072
	global_load_dwordx4 v[214:217], v152, s[74:75] offset:0
	global_load_dwordx4 v[218:221], v152, s[74:75] offset:1024
	global_load_dwordx4 v[222:225], v152, s[74:75] offset:2048
	global_load_dwordx4 v[226:229], v152, s[74:75] offset:3072
	global_load_dwordx4 v[170:173], v152, s[72:73] offset:0
	global_load_dwordx4 v[174:177], v152, s[72:73] offset:1024
	global_load_dwordx4 v[178:181], v152, s[72:73] offset:2048
	global_load_dwordx4 v[182:185], v152, s[72:73] offset:3072
	s_waitcnt vmcnt(0)
	v_add_f32_e32 v214, 1.0, v214
	v_add_f32_e32 v215, 1.0, v215
	v_add_f32_e32 v216, 1.0, v216
	v_add_f32_e32 v217, 1.0, v217
	v_add_f32_e32 v218, 1.0, v218
	v_add_f32_e32 v219, 1.0, v219
	v_add_f32_e32 v220, 1.0, v220
	v_add_f32_e32 v221, 1.0, v221
	v_add_f32_e32 v222, 1.0, v222
	v_add_f32_e32 v223, 1.0, v223
	v_add_f32_e32 v224, 1.0, v224
	v_add_f32_e32 v225, 1.0, v225
	v_add_f32_e32 v226, 1.0, v226
	v_add_f32_e32 v227, 1.0, v227
	v_add_f32_e32 v228, 1.0, v228
	v_add_f32_e32 v229, 1.0, v229
	v_mul_f32_e32 v154, v154, v214
	v_mul_f32_e32 v155, v155, v215
	v_mul_f32_e32 v156, v156, v216
	v_mul_f32_e32 v157, v157, v217
	v_mul_f32_e32 v158, v158, v218
	v_mul_f32_e32 v159, v159, v219
	v_mul_f32_e32 v160, v160, v220
	v_mul_f32_e32 v161, v161, v221
	v_mul_f32_e32 v162, v162, v222
	v_mul_f32_e32 v163, v163, v223
	v_mul_f32_e32 v164, v164, v224
	v_mul_f32_e32 v165, v165, v225
	v_mul_f32_e32 v166, v166, v226
	v_mul_f32_e32 v167, v167, v227
	v_mul_f32_e32 v168, v168, v228
	v_mul_f32_e32 v169, v169, v229

; DI unsigned pack2(float lo, float hi) { f32x2_t v = {lo, hi}; bf16x2_t r = __builtin_convertvector(v, bf16x2_t); return __builtin_bit_cast(unsigned, r); }
; DI void phase_norm(const Params& p, int layer, int which  , int nrows) {
;     ...
; #pragma unroll
;     for (int i = 0; i < 4; ++i) {
;       ss0 += v[0][i].x * v[0][i].x + v[0][i].y * v[0][i].y + v[0][i].z * v[0][i].z + v[0][i].w * v[0][i].w;
;       ss1 += v[1][i].x * v[1][i].x + v[1][i].y * v[1][i].y + v[1][i].z * v[1][i].z + v[1][i].w * v[1][i].w;
;     }
;     ss0 = wave_sum(ss0); ss1 = wave_sum(ss1);
;     const float rstd0 = rsqrtf(ss0 * (1.0f / D) + 1e-6f), rstd1 = rsqrtf(ss1 * (1.0f / D) + 1e-6f);
; #pragma unroll
;     for (int k = 0; k < 2; ++k) {
;       const float rstd = k == 0 ? rstd0 : rstd1;
; #pragma unroll
;       for (int i = 0; i < 4; ++i) {
;         const int col = 4 * (lane + 64 * i);
;         float y0 = v[k][i].x * rstd * gg[i].x * (1.f + s4[i].x) + h4[i].x;
;         float y1 = v[k][i].y * rstd * gg[i].y * (1.f + s4[i].y) + h4[i].y;
;         float y2 = v[k][i].z * rstd * gg[i].z * (1.f + s4[i].z) + h4[i].z;
;         float y3 = v[k][i].w * rstd * gg[i].w * (1.f + s4[i].w) + h4[i].w;
;         uint2 w; w.x = pack2(y0, y1); w.y = pack2(y2, y3);
;         *(uint2*)(H + (size_t)(row + k) * D + col) = w;
.Lnm_nj_20:
	s_lshl_b32 s0, s57, 6
	s_add_u32 s0, s0, 0x15980000
	s_add_u32 s66, s24, s0
	s_addc_u32 s67, s25, 0
	v_mul_f32_e32 v128, v64, v64
	v_fmac_f32_e32 v128, v65, v65
	v_fmac_f32_e32 v128, v66, v66
	v_fmac_f32_e32 v128, v67, v67
	v_fmac_f32_e32 v128, v68, v68
	v_fmac_f32_e32 v128, v69, v69
	v_fmac_f32_e32 v128, v70, v70
	v_fmac_f32_e32 v128, v71, v71
	v_fmac_f32_e32 v128, v72, v72
	v_fmac_f32_e32 v128, v73, v73
	v_fmac_f32_e32 v128, v74, v74
	v_fmac_f32_e32 v128, v75, v75
	v_fmac_f32_e32 v128, v76, v76
	v_fmac_f32_e32 v128, v77, v77
	v_fmac_f32_e32 v128, v78, v78
	v_fmac_f32_e32 v128, v79, v79
	v_mul_f32_e32 v129, v80, v80
	v_fmac_f32_e32 v129, v81, v81
	v_fmac_f32_e32 v129, v82, v82
	v_fmac_f32_e32 v129, v83, v83
	v_fmac_f32_e32 v129, v84, v84
	v_fmac_f32_e32 v129, v85, v85
	v_fmac_f32_e32 v129, v86, v86
	v_fmac_f32_e32 v129, v87, v87
	v_fmac_f32_e32 v129, v88, v88
	v_fmac_f32_e32 v129, v89, v89
	v_fmac_f32_e32 v129, v90, v90
	v_fmac_f32_e32 v129, v91, v91
	v_fmac_f32_e32 v129, v92, v92
	v_fmac_f32_e32 v129, v93, v93
	v_fmac_f32_e32 v129, v94, v94
	v_fmac_f32_e32 v129, v95, v95
	v_mul_f32_e32 v130, v96, v96
	v_fmac_f32_e32 v130, v97, v97
	v_fmac_f32_e32 v130, v98, v98
	v_fmac_f32_e32 v130, v99, v99
	v_fmac_f32_e32 v130, v100, v100
	v_fmac_f32_e32 v130, v101, v101
	v_fmac_f32_e32 v130, v102, v102
	v_fmac_f32_e32 v130, v103, v103
	v_fmac_f32_e32 v130, v104, v104
	v_fmac_f32_e32 v130, v105, v105
	v_fmac_f32_e32 v130, v106, v106
	v_fmac_f32_e32 v130, v107, v107
	v_fmac_f32_e32 v130, v108, v108
	v_fmac_f32_e32 v130, v109, v109
	v_fmac_f32_e32 v130, v110, v110
	v_fmac_f32_e32 v130, v111, v111
	v_mul_f32_e32 v131, v112, v112
	v_fmac_f32_e32 v131, v113, v113
	v_fmac_f32_e32 v131, v114, v114
	v_fmac_f32_e32 v131, v115, v115
	v_fmac_f32_e32 v131, v116, v116
	v_fmac_f32_e32 v131, v117, v117
	v_fmac_f32_e32 v131, v118, v118
	v_fmac_f32_e32 v131, v119, v119
	v_fmac_f32_e32 v131, v120, v120
	v_fmac_f32_e32 v131, v121, v121
	v_fmac_f32_e32 v131, v122, v122
	v_fmac_f32_e32 v131, v123, v123
	v_fmac_f32_e32 v131, v124, v124
	v_fmac_f32_e32 v131, v125, v125
	v_fmac_f32_e32 v131, v126, v126
	v_fmac_f32_e32 v131, v127, v127
	v_add_f32_dpp v128, v128, v128 quad_perm:[1,0,3,2] row_mask:0xf bank_mask:0xf
	v_add_f32_dpp v129, v129, v129 quad_perm:[1,0,3,2] row_mask:0xf bank_mask:0xf
	v_add_f32_dpp v130, v130, v130 quad_perm:[1,0,3,2] row_mask:0xf bank_mask:0xf
	v_add_f32_dpp v131, v131, v131 quad_perm:[1,0,3,2] row_mask:0xf bank_mask:0xf
	v_add_f32_dpp v128, v128, v128 quad_perm:[2,3,0,1] row_mask:0xf bank_mask:0xf
	v_add_f32_dpp v129, v129, v129 quad_perm:[2,3,0,1] row_mask:0xf bank_mask:0xf
	v_add_f32_dpp v130, v130, v130 quad_perm:[2,3,0,1] row_mask:0xf bank_mask:0xf
	v_add_f32_dpp v131, v131, v131 quad_perm:[2,3,0,1] row_mask:0xf bank_mask:0xf
	v_add_f32_dpp v128, v128, v128 row_half_mirror row_mask:0xf bank_mask:0xf
	v_add_f32_dpp v129, v129, v129 row_half_mirror row_mask:0xf bank_mask:0xf
	v_add_f32_dpp v130, v130, v130 row_half_mirror row_mask:0xf bank_mask:0xf
	v_add_f32_dpp v131, v131, v131 row_half_mirror row_mask:0xf bank_mask:0xf
	v_add_f32_dpp v128, v128, v128 row_mirror row_mask:0xf bank_mask:0xf
	v_add_f32_dpp v129, v129, v129 row_mirror row_mask:0xf bank_mask:0xf
	v_add_f32_dpp v130, v130, v130 row_mirror row_mask:0xf bank_mask:0xf
	v_add_f32_dpp v131, v131, v131 row_mirror row_mask:0xf bank_mask:0xf
	s_nop 1
	v_readlane_b32 s82, v128, 0
	v_readlane_b32 s83, v128, 16
	v_readlane_b32 s84, v128, 32
	v_readlane_b32 s85, v128, 48
	s_nop 1
	v_mov_b32_e32 v132, s82
	v_add_f32_e32 v132, s83, v132
	v_add_f32_e32 v132, s84, v132
	v_add_f32_e32 v132, s85, v132
	v_readlane_b32 s82, v129, 0
	v_readlane_b32 s83, v129, 16
	v_readlane_b32 s84, v129, 32
	v_readlane_b32 s85, v129, 48
	s_nop 1
	v_mov_b32_e32 v133, s82
	v_add_f32_e32 v133, s83, v133
	v_add_f32_e32 v133, s84, v133
	v_add_f32_e32 v133, s85, v133
	v_readlane_b32 s82, v130, 0
	v_readlane_b32 s83, v130, 16
	v_readlane_b32 s84, v130, 32
	v_readlane_b32 s85, v130, 48
	s_nop 1
	v_mov_b32_e32 v134, s82
	v_add_f32_e32 v134, s83, v134
	v_add_f32_e32 v134, s84, v134
	v_add_f32_e32 v134, s85, v134
	v_readlane_b32 s82, v131, 0
	v_readlane_b32 s83, v131, 16
	v_readlane_b32 s84, v131, 32
	v_readlane_b32 s85, v131, 48
	s_nop 1
	v_mov_b32_e32 v135, s82
	v_add_f32_e32 v135, s83, v135
	v_add_f32_e32 v135, s84, v135
	v_add_f32_e32 v135, s85, v135
	s_mov_b32 s0, 0x3a800000
	v_fma_f32 v132, v132, s0, v153
	v_fma_f32 v133, v133, s0, v153
	v_fma_f32 v134, v134, s0, v153
	v_fma_f32 v135, v135, s0, v153
	v_rsq_f32_e32 v128, v132
	v_rsq_f32_e32 v129, v133
	v_rsq_f32_e32 v130, v134
	v_rsq_f32_e32 v131, v135
	v_mul_f32_e32 v64, v64, v128
	v_mul_f32_e32 v65, v65, v128
	v_mul_f32_e32 v66, v66, v128
	v_mul_f32_e32 v67, v67, v128
	v_fma_f32 v64, v64, v154, v170
	v_fma_f32 v65, v65, v155, v171
	v_fma_f32 v66, v66, v156, v172
	v_fma_f32 v67, v67, v157, v173
	v_cvt_pk_bf16_f32 v238, v64, v65
	v_cvt_pk_bf16_f32 v239, v66, v67
	global_store_dwordx2 v148, v[238:239], s[66:67]
	v_mul_f32_e32 v68, v68, v128
	v_mul_f32_e32 v69, v69, v128
	v_mul_f32_e32 v70, v70, v128
	v_mul_f32_e32 v71, v71, v128
	v_fma_f32 v68, v68, v158, v174
	v_fma_f32 v69, v69, v159, v175
	v_fma_f32 v70, v70, v160, v176
	v_fma_f32 v71, v71, v161, v177
	v_cvt_pk_bf16_f32 v240, v68, v69
	v_cvt_pk_bf16_f32 v241, v70, v71
	global_store_dwordx2 v149, v[240:241], s[66:67]
	v_mul_f32_e32 v72, v72, v128
	v_mul_f32_e32 v73, v73, v128
; DI unsigned pack2(float lo, float hi) { f32x2_t v = {lo, hi}; bf16x2_t r = __builtin_convertvector(v, bf16x2_t); return __builtin_bit_cast(unsigned, r); }
; DI void phase_norm(const Params& p, int layer, int which  , int nrows) {
;     ...
; #pragma unroll
;     for (int k = 0; k < 2; ++k) {
;       const float rstd = k == 0 ? rstd0 : rstd1;
; #pragma unroll
;       for (int i = 0; i < 4; ++i) {
;         const int col = 4 * (lane + 64 * i);
;         float y0 = v[k][i].x * rstd * gg[i].x * (1.f + s4[i].x) + h4[i].x;
;         float y1 = v[k][i].y * rstd * gg[i].y * (1.f + s4[i].y) + h4[i].y;
;         float y2 = v[k][i].z * rstd * gg[i].z * (1.f + s4[i].z) + h4[i].z;
;         float y3 = v[k][i].w * rstd * gg[i].w * (1.f + s4[i].w) + h4[i].w;
;         uint2 w; w.x = pack2(y0, y1); w.y = pack2(y2, y3);
;         *(uint2*)(H + (size_t)(row + k) * D + col) = w;
;       }
;     }
	v_mul_f32_e32 v74, v74, v128
	v_mul_f32_e32 v75, v75, v128
	v_fma_f32 v72, v72, v162, v178
	v_fma_f32 v73, v73, v163, v179
	v_fma_f32 v74, v74, v164, v180
	v_fma_f32 v75, v75, v165, v181
	v_cvt_pk_bf16_f32 v242, v72, v73
	v_cvt_pk_bf16_f32 v243, v74, v75
	global_store_dwordx2 v150, v[242:243], s[66:67]
	v_mul_f32_e32 v76, v76, v128
	v_mul_f32_e32 v77, v77, v128
	v_mul_f32_e32 v78, v78, v128
	v_mul_f32_e32 v79, v79, v128
	v_fma_f32 v76, v76, v166, v182
	v_fma_f32 v77, v77, v167, v183
	v_fma_f32 v78, v78, v168, v184
	v_fma_f32 v79, v79, v169, v185
	v_cvt_pk_bf16_f32 v244, v76, v77
	v_cvt_pk_bf16_f32 v245, v78, v79
	global_store_dwordx2 v151, v[244:245], s[66:67]
	v_mul_f32_e32 v80, v80, v129
	v_mul_f32_e32 v81, v81, v129
	v_mul_f32_e32 v82, v82, v129
	v_mul_f32_e32 v83, v83, v129
	v_fma_f32 v80, v80, v154, v170
	v_fma_f32 v81, v81, v155, v171
	v_fma_f32 v82, v82, v156, v172
	v_fma_f32 v83, v83, v157, v173
	v_cvt_pk_bf16_f32 v246, v80, v81
	v_cvt_pk_bf16_f32 v247, v82, v83
	global_store_dwordx2 v148, v[246:247], s[66:67] offset:64
	v_mul_f32_e32 v84, v84, v129
	v_mul_f32_e32 v85, v85, v129
	v_mul_f32_e32 v86, v86, v129
	v_mul_f32_e32 v87, v87, v129
	v_fma_f32 v84, v84, v158, v174
	v_fma_f32 v85, v85, v159, v175
	v_fma_f32 v86, v86, v160, v176
	v_fma_f32 v87, v87, v161, v177
	v_cvt_pk_bf16_f32 v248, v84, v85
	v_cvt_pk_bf16_f32 v249, v86, v87
	global_store_dwordx2 v149, v[248:249], s[66:67] offset:64
	v_mul_f32_e32 v88, v88, v129
	v_mul_f32_e32 v89, v89, v129
	v_mul_f32_e32 v90, v90, v129
	v_mul_f32_e32 v91, v91, v129
	v_fma_f32 v88, v88, v162, v178
	v_fma_f32 v89, v89, v163, v179
	v_fma_f32 v90, v90, v164, v180
	v_fma_f32 v91, v91, v165, v181
	v_cvt_pk_bf16_f32 v238, v88, v89
	v_cvt_pk_bf16_f32 v239, v90, v91
	global_store_dwordx2 v150, v[238:239], s[66:67] offset:64
	v_mul_f32_e32 v92, v92, v129
	v_mul_f32_e32 v93, v93, v129
	v_mul_f32_e32 v94, v94, v129
	v_mul_f32_e32 v95, v95, v129
	v_fma_f32 v92, v92, v166, v182
	v_fma_f32 v93, v93, v167, v183
	v_fma_f32 v94, v94, v168, v184
	v_fma_f32 v95, v95, v169, v185
	v_cvt_pk_bf16_f32 v240, v92, v93
	v_cvt_pk_bf16_f32 v241, v94, v95
	global_store_dwordx2 v151, v[240:241], s[66:67] offset:64
	v_mul_f32_e32 v96, v96, v130
	v_mul_f32_e32 v97, v97, v130
	v_mul_f32_e32 v98, v98, v130
	v_mul_f32_e32 v99, v99, v130
	v_fma_f32 v96, v96, v154, v170
	v_fma_f32 v97, v97, v155, v171
	v_fma_f32 v98, v98, v156, v172
	v_fma_f32 v99, v99, v157, v173
	v_cvt_pk_bf16_f32 v242, v96, v97
	v_cvt_pk_bf16_f32 v243, v98, v99
	global_store_dwordx2 v148, v[242:243], s[66:67] offset:128
	v_mul_f32_e32 v100, v100, v130
	v_mul_f32_e32 v101, v101, v130
	v_mul_f32_e32 v102, v102, v130
	v_mul_f32_e32 v103, v103, v130
	v_fma_f32 v100, v100, v158, v174
	v_fma_f32 v101, v101, v159, v175
	v_fma_f32 v102, v102, v160, v176
	v_fma_f32 v103, v103, v161, v177
	v_cvt_pk_bf16_f32 v244, v100, v101
	v_cvt_pk_bf16_f32 v245, v102, v103
	global_store_dwordx2 v149, v[244:245], s[66:67] offset:128
	v_mul_f32_e32 v104, v104, v130
	v_mul_f32_e32 v105, v105, v130
	v_mul_f32_e32 v106, v106, v130
	v_mul_f32_e32 v107, v107, v130
	v_fma_f32 v104, v104, v162, v178
	v_fma_f32 v105, v105, v163, v179
	v_fma_f32 v106, v106, v164, v180
	v_fma_f32 v107, v107, v165, v181
	v_cvt_pk_bf16_f32 v246, v104, v105
	v_cvt_pk_bf16_f32 v247, v106, v107
	global_store_dwordx2 v150, v[246:247], s[66:67] offset:128
	v_mul_f32_e32 v108, v108, v130
	v_mul_f32_e32 v109, v109, v130
	v_mul_f32_e32 v110, v110, v130
	v_mul_f32_e32 v111, v111, v130
	v_fma_f32 v108, v108, v166, v182
	v_fma_f32 v109, v109, v167, v183
	v_fma_f32 v110, v110, v168, v184
	v_fma_f32 v111, v111, v169, v185
	v_cvt_pk_bf16_f32 v248, v108, v109
	v_cvt_pk_bf16_f32 v249, v110, v111
	global_store_dwordx2 v151, v[248:249], s[66:67] offset:128
	v_mul_f32_e32 v112, v112, v131
	v_mul_f32_e32 v113, v113, v131
	v_mul_f32_e32 v114, v114, v131
	v_mul_f32_e32 v115, v115, v131
	v_fma_f32 v112, v112, v154, v170
	v_fma_f32 v113, v113, v155, v171
	v_fma_f32 v114, v114, v156, v172
	v_fma_f32 v115, v115, v157, v173
	v_cvt_pk_bf16_f32 v238, v112, v113
	v_cvt_pk_bf16_f32 v239, v114, v115
	global_store_dwordx2 v148, v[238:239], s[66:67] offset:192
	v_mul_f32_e32 v116, v116, v131
	v_mul_f32_e32 v117, v117, v131
	v_mul_f32_e32 v118, v118, v131
	v_mul_f32_e32 v119, v119, v131
	v_fma_f32 v116, v116, v158, v174
	v_fma_f32 v117, v117, v159, v175
	v_fma_f32 v118, v118, v160, v176
	v_fma_f32 v119, v119, v161, v177
	v_cvt_pk_bf16_f32 v240, v116, v117
	v_cvt_pk_bf16_f32 v241, v118, v119
	global_store_dwordx2 v149, v[240:241], s[66:67] offset:192
	v_mul_f32_e32 v120, v120, v131
	v_mul_f32_e32 v121, v121, v131
	v_mul_f32_e32 v122, v122, v131
	v_mul_f32_e32 v123, v123, v131
	v_fma_f32 v120, v120, v162, v178
	v_fma_f32 v121, v121, v163, v179
	v_fma_f32 v122, v122, v164, v180
	v_fma_f32 v123, v123, v165, v181
	v_cvt_pk_bf16_f32 v242, v120, v121
	v_cvt_pk_bf16_f32 v243, v122, v123
	global_store_dwordx2 v150, v[242:243], s[66:67] offset:192
	v_mul_f32_e32 v124, v124, v131
	v_mul_f32_e32 v125, v125, v131
	v_mul_f32_e32 v126, v126, v131
	v_mul_f32_e32 v127, v127, v131
	v_fma_f32 v124, v124, v166, v182
	v_fma_f32 v125, v125, v167, v183
	v_fma_f32 v126, v126, v168, v184
	v_fma_f32 v127, v127, v169, v185
	v_cvt_pk_bf16_f32 v244, v124, v125
	v_cvt_pk_bf16_f32 v245, v126, v127
	global_store_dwordx2 v151, v[244:245], s[66:67] offset:192
	s_mov_b32 s54, s80
	s_cmp_lt_u32 s81, s78
	s_cbranch_scc1 .Lnm_loop_8
